# UP phases: column-tile order remapped (pn -> (pn&3)*4+(pn>>2), rotated by row-block group) so concurrent tiles write all 512-B slots of the 8-KB ubuf rows
# speedup vs baseline: 1.0220x; 1.0169x over previous
.LBB0_321:
	s_lshl_b32 s3, s3, 3
	v_cvt_f32_u32_e32 v0, s3
	s_sub_i32 s9, 0, s3
	s_ashr_i32 s8, s10, 3
	s_add_i32 s8, s11, s8
	v_rcp_iflag_f32_e32 v0, v0
	s_abs_i32 s11, s8
	s_ashr_i32 s10, s8, 31
	v_mul_f32_e32 v0, 0x4f7ffffe, v0
	v_cvt_u32_f32_e32 v0, v0
	s_nop 0
	v_readfirstlane_b32 s12, v0
	s_mul_i32 s9, s9, s12
	s_mul_hi_u32 s9, s12, s9
	s_add_i32 s12, s12, s9
	s_mul_hi_u32 s9, s11, s12
	s_mul_i32 s12, s9, s3
	s_sub_i32 s11, s11, s12
	s_add_i32 s13, s9, 1
	s_sub_i32 s12, s11, s3
	s_cmp_ge_u32 s11, s3
	s_cselect_b32 s9, s13, s9
	s_cselect_b32 s11, s12, s11
	s_add_i32 s12, s9, 1
	s_cmp_ge_u32 s11, s3
	s_cselect_b32 s9, s12, s9
	s_xor_b32 s9, s9, s10
	s_sub_i32 s9, s9, s10
	s_lshl_b32 s10, s9, 3
	s_sub_i32 s2, s2, s10
	s_min_i32 s11, s2, 8
	s_sext_i32_i16 s2, s11
	v_cvt_f32_i32_e32 v0, s2
	s_mul_i32 s9, s9, s3
	s_sub_i32 s8, s8, s9
	s_sext_i32_i16 s3, s8
	v_cvt_f32_i32_e32 v1, s3
	v_rcp_iflag_f32_e32 v2, v0
	s_xor_b32 s2, s3, s2
	s_ashr_i32 s2, s2, 30
	s_or_b32 s9, s2, 1
	v_mul_f32_e32 v2, v1, v2
	v_trunc_f32_e32 v2, v2
	v_fma_f32 v1, -v2, v0, v1
	v_cvt_i32_f32_e32 v2, v2
	v_cmp_ge_f32_e64 s[2:3], |v1|, |v0|
	s_and_b64 s[2:3], s[2:3], exec
	s_cselect_b32 s2, s9, 0
	v_readfirstlane_b32 s3, v2
	s_add_i32 s2, s3, s2
	s_mul_i32 s3, s2, s11
	s_sub_i32 s3, s8, s3
	s_sext_i32_i16 s3, s3
	s_add_i32 s38, s10, s3
	s_and_b64 s[8:9], s[6:7], exec
	s_cselect_b32 s29, s86, 5
	s_cselect_b32 s3, s49, s93
	s_cselect_b32 s8, s48, s92
	s_cmp_lg_u32 s29, 3
	s_cbranch_scc1 .Lpn_keep0
	s_and_b32 s9, s2, 3
	s_lshl_b32 s9, s9, 2
	s_lshr_b32 s10, s2, 2
	s_or_b32 s2, s9, s10
	s_lshr_b32 s9, s38, 3
	s_add_i32 s2, s2, s9
	s_and_b32 s2, s2, 15
.Lpn_keep0:
	s_ashr_i32 s9, s38, 31
	s_mul_i32 s9, s58, s9
	s_mul_hi_u32 s10, s58, s38
	s_add_i32 s9, s10, s9
	s_mul_i32 s10, s59, s38
	s_add_i32 s9, s9, s10
	s_mul_i32 s10, s58, s38
	s_add_u32 s60, s8, s10
	s_addc_u32 s61, s3, s9
	s_and_b64 s[6:7], s[6:7], exec
	s_sext_i32_i16 s24, s2
	s_cselect_b32 s6, s21, s51
	s_cselect_b32 s7, s20, s50
	s_bfe_i64 s[2:3], s[2:3], 0x100000
	s_mul_i32 s3, s58, s3
	s_mul_hi_u32 s8, s58, s2
	s_add_i32 s3, s8, s3
	s_mul_i32 s8, s59, s2
	s_add_i32 s3, s3, s8
	s_mul_i32 s2, s58, s2
	s_add_u32 s62, s7, s2
	s_addc_u32 s63, s6, s3
	s_mov_b64 s[6:7], 0

.LBB0_385:
	s_lshl_b32 s10, s13, 3
	s_abs_i32 s11, s10
	v_cvt_f32_u32_e32 v128, s11
	s_sub_i32 s39, 0, s11
	s_ashr_i32 s13, s28, 3
	s_add_i32 s13, s37, s13
	v_rcp_iflag_f32_e32 v128, v128
	s_abs_i32 s37, s13
	s_xor_b32 s28, s13, s10
	s_ashr_i32 s28, s28, 31
	v_mul_f32_e32 v128, 0x4f7ffffe, v128
	v_cvt_u32_f32_e32 v128, v128
	s_nop 0
	v_readfirstlane_b32 s40, v128
	s_mul_i32 s39, s39, s40
	s_mul_hi_u32 s39, s40, s39
	s_add_i32 s40, s40, s39
	s_mul_hi_u32 s39, s37, s40
	s_mul_i32 s40, s39, s11
	s_sub_i32 s37, s37, s40
	s_add_i32 s41, s39, 1
	s_sub_i32 s40, s37, s11
	s_cmp_ge_u32 s37, s11
	s_cselect_b32 s39, s41, s39
	s_cselect_b32 s37, s40, s37
	s_add_i32 s40, s39, 1
	s_cmp_ge_u32 s37, s11
	s_cselect_b32 s11, s40, s39
	s_xor_b32 s11, s11, s28
	s_sub_i32 s11, s11, s28
	s_lshl_b32 s28, s11, 3
	s_sub_i32 s12, s12, s28
	s_min_i32 s12, s12, 8
	s_abs_i32 s37, s12
	v_cvt_f32_u32_e32 v128, s37
	s_sub_i32 s39, 0, s37
	s_mul_i32 s11, s11, s10
	s_sub_i32 s10, s13, s11
	v_rcp_iflag_f32_e32 v128, v128
	s_abs_i32 s11, s10
	s_xor_b32 s13, s10, s12
	s_ashr_i32 s13, s13, 31
	v_mul_f32_e32 v128, 0x4f7ffffe, v128
	v_cvt_u32_f32_e32 v128, v128
	s_nop 0
	v_readfirstlane_b32 s40, v128
	s_mul_i32 s39, s39, s40
	s_mul_hi_u32 s39, s40, s39
	s_add_i32 s40, s40, s39
	s_mul_hi_u32 s39, s11, s40
	s_mul_i32 s40, s39, s37
	s_sub_i32 s11, s11, s40
	s_add_i32 s41, s39, 1
	s_sub_i32 s40, s11, s37
	s_cmp_ge_u32 s11, s37
	s_cselect_b32 s39, s41, s39
	s_cselect_b32 s11, s40, s11
	s_add_i32 s40, s39, 1
	s_cmp_ge_u32 s11, s37
	s_cselect_b32 s11, s40, s39
	s_xor_b32 s11, s11, s13
	s_sub_i32 s37, s11, s13
	s_mul_i32 s11, s37, s12
	s_sub_i32 s10, s10, s11
	s_add_i32 s28, s10, s28
	s_and_b64 s[10:11], s[8:9], exec
	s_cselect_b32 s39, s42, 5
	s_cselect_b32 s10, s49, s93
	s_cselect_b32 s11, s48, s92
	s_cmp_lg_u32 s39, 3
	s_cbranch_scc1 .Lpn_keep1
	s_and_b32 s12, s37, 3
	s_lshl_b32 s12, s12, 2
	s_lshr_b32 s13, s37, 2
	s_or_b32 s37, s12, s13
	s_lshr_b32 s12, s28, 3
	s_add_i32 s37, s37, s12
	s_and_b32 s37, s37, 15
.Lpn_keep1:
	s_ashr_i32 s12, s28, 31
	s_mul_i32 s12, s58, s12
	s_mul_hi_u32 s13, s58, s28
	s_add_i32 s12, s13, s12
	s_mul_i32 s13, s59, s28
	s_add_i32 s12, s12, s13
	s_mul_i32 s13, s58, s28
	s_add_u32 s84, s11, s13
	s_addc_u32 s85, s10, s12
	v_readlane_b32 s10, v254, 22
	s_and_b64 s[8:9], s[8:9], exec
	v_readlane_b32 s11, v254, 23
	s_cselect_b32 s8, s21, s11
	s_cselect_b32 s9, s20, s10
	s_ashr_i32 s10, s37, 31
	s_mul_i32 s10, s58, s10
	s_mul_hi_u32 s11, s58, s37
	s_add_i32 s10, s11, s10
	s_mul_i32 s11, s59, s37
	s_add_i32 s10, s10, s11
	s_mul_i32 s11, s58, s37
	s_add_u32 s86, s9, s11
	s_addc_u32 s87, s8, s10
	s_mov_b64 s[8:9], 0
